# GLU: 7 of 8 z row-group loads issued at the tile head (before the K loop) into registers untouched by the loop; packed GLU/S3 epilogues kept
# speedup vs baseline: 1.0078x; 1.0078x over previous
; template <bool SP2 = true, class Epi, class Sched>
; __device__ __forceinline__ void gemm_phase(LAS unsigned char* lds, const int K, const int lda, const int ldb, const Sched& S, const Epi& E) {
;     ...
; #pragma unroll
;         for (int a = 0; a < 2; ++a)
; #pragma unroll
;             for (int b = 0; b < 2; ++b)
; #pragma unroll
;                 for (int m = 0; m < 4; ++m)
; #pragma unroll
;                     for (int n = 0; n < 2; ++n) acc[a][b][m][n] = (f32x4){0.f, 0.f, 0.f, 0.f};
;     __device__ __forceinline__ void operator()(const AccT& acc, const Unit& u, int wr, int wc, int fr, int fq) const {
;     ...
;                 const u32x4 z = *(const u32x4*)(PROJ + (size_t)row * PP + C_ZS + lc);
.LBB0_605:
	v_lshl_or_b32 v252, s38, 7, v166
	v_lshl_add_u32 v253, s37, 8, v164
	v_mul_u32_u24_e32 v253, 0x2800, v253
	v_lshl_add_u32 v253, v252, 1, v253
	v_add_u32_e32 v253, 0x10a02000, v253
	v_mov_b32_e32 v216, v253
	global_load_dwordx4 v[216:219], v216, s[6:7]
	v_add_u32_e32 v220, 0x28000, v253
	global_load_dwordx4 v[220:223], v220, s[6:7]
	v_add_u32_e32 v226, 0x50000, v253
	global_load_dwordx4 v[226:229], v226, s[6:7]
	v_add_u32_e32 v236, 0x78000, v253
	global_load_dwordx4 v[236:239], v236, s[6:7]
	v_add_u32_e32 v240, 0x140000, v253
	global_load_dwordx4 v[240:243], v240, s[6:7]
	v_add_u32_e32 v244, 0x168000, v253
	global_load_dwordx4 v[244:247], v244, s[6:7]
	v_add_u32_e32 v248, 0x190000, v253
	global_load_dwordx4 v[248:251], v248, s[6:7]
	s_add_u32 s30, s30, 0x40080
	s_addc_u32 s31, s31, 0
	s_add_u32 s23, s82, 0x100
	v_mov_b32_e32 v0, 0
	s_addc_u32 s25, s83, 0
	s_mov_b32 s48, -2
	v_mov_b32_e32 v1, v0
	v_mov_b32_e32 v2, v0
	v_mov_b32_e32 v3, v0
	v_mov_b32_e32 v4, v0
	v_mov_b32_e32 v5, v0
	v_mov_b32_e32 v6, v0
	v_mov_b32_e32 v7, v0
	v_mov_b32_e32 v32, v0
	v_mov_b32_e32 v33, v0
	v_mov_b32_e32 v34, v0
	v_mov_b32_e32 v35, v0
	v_mov_b32_e32 v36, v0
	v_mov_b32_e32 v37, v0
	v_mov_b32_e32 v38, v0
	v_mov_b32_e32 v39, v0
	v_mov_b32_e32 v48, v0
	v_mov_b32_e32 v49, v0
	v_mov_b32_e32 v50, v0
	v_mov_b32_e32 v51, v0
	v_mov_b32_e32 v52, v0
	v_mov_b32_e32 v53, v0
	v_mov_b32_e32 v54, v0
	v_mov_b32_e32 v55, v0
	v_mov_b32_e32 v64, v0
	v_mov_b32_e32 v65, v0
	v_mov_b32_e32 v66, v0
	v_mov_b32_e32 v67, v0
	v_mov_b32_e32 v68, v0
	v_mov_b32_e32 v69, v0
	v_mov_b32_e32 v70, v0
	v_mov_b32_e32 v71, v0
	v_mov_b32_e32 v8, v0
	v_mov_b32_e32 v9, v0
	v_mov_b32_e32 v10, v0
	v_mov_b32_e32 v11, v0
	v_mov_b32_e32 v12, v0
	v_mov_b32_e32 v13, v0
	v_mov_b32_e32 v14, v0
	v_mov_b32_e32 v15, v0
	v_mov_b32_e32 v40, v0
	v_mov_b32_e32 v41, v0
	v_mov_b32_e32 v42, v0
	v_mov_b32_e32 v43, v0
	v_mov_b32_e32 v44, v0
	v_mov_b32_e32 v45, v0
	v_mov_b32_e32 v46, v0
	v_mov_b32_e32 v47, v0
	v_mov_b32_e32 v56, v0
	v_mov_b32_e32 v57, v0
	v_mov_b32_e32 v58, v0
	v_mov_b32_e32 v59, v0
	v_mov_b32_e32 v60, v0
	v_mov_b32_e32 v61, v0
	v_mov_b32_e32 v62, v0
	v_mov_b32_e32 v63, v0
	v_mov_b32_e32 v72, v0
	v_mov_b32_e32 v73, v0
	v_mov_b32_e32 v74, v0
	v_mov_b32_e32 v75, v0
	v_mov_b32_e32 v76, v0
	v_mov_b32_e32 v77, v0
	v_mov_b32_e32 v78, v0
	v_mov_b32_e32 v79, v0
	v_mov_b32_e32 v80, v0
	v_mov_b32_e32 v81, v0
	v_mov_b32_e32 v82, v0
	v_mov_b32_e32 v83, v0
	v_mov_b32_e32 v84, v0
	v_mov_b32_e32 v85, v0
	v_mov_b32_e32 v86, v0
	v_mov_b32_e32 v87, v0
	v_mov_b32_e32 v96, v0
	v_mov_b32_e32 v97, v0
	v_mov_b32_e32 v98, v0
	v_mov_b32_e32 v99, v0
	v_mov_b32_e32 v100, v0
	v_mov_b32_e32 v101, v0
	v_mov_b32_e32 v102, v0
	v_mov_b32_e32 v103, v0
	v_mov_b32_e32 v112, v0
	v_mov_b32_e32 v113, v0
	v_mov_b32_e32 v114, v0
	v_mov_b32_e32 v115, v0
	v_mov_b32_e32 v116, v0
	v_mov_b32_e32 v117, v0
	v_mov_b32_e32 v118, v0
	v_mov_b32_e32 v119, v0
	v_mov_b32_e32 v132, v0
	v_mov_b32_e32 v133, v0
	v_mov_b32_e32 v134, v0
	v_mov_b32_e32 v135, v0
	v_mov_b32_e32 v136, v0
	v_mov_b32_e32 v137, v0
	v_mov_b32_e32 v138, v0
	v_mov_b32_e32 v139, v0
	v_mov_b32_e32 v88, v0
	v_mov_b32_e32 v89, v0
	v_mov_b32_e32 v90, v0
	v_mov_b32_e32 v91, v0
	v_mov_b32_e32 v92, v0
	v_mov_b32_e32 v93, v0
	v_mov_b32_e32 v94, v0
	v_mov_b32_e32 v95, v0
	v_mov_b32_e32 v104, v0
	v_mov_b32_e32 v105, v0
	v_mov_b32_e32 v106, v0
	v_mov_b32_e32 v107, v0
	v_mov_b32_e32 v108, v0
	v_mov_b32_e32 v109, v0
	v_mov_b32_e32 v110, v0
	v_mov_b32_e32 v111, v0
	v_mov_b32_e32 v120, v0
	v_mov_b32_e32 v121, v0
	v_mov_b32_e32 v122, v0
	v_mov_b32_e32 v123, v0
	v_mov_b32_e32 v124, v0
	v_mov_b32_e32 v125, v0
	v_mov_b32_e32 v126, v0
	v_mov_b32_e32 v127, v0
	v_mov_b32_e32 v140, v0
	v_mov_b32_e32 v141, v0
	v_mov_b32_e32 v142, v0
	v_mov_b32_e32 v143, v0
	v_mov_b32_e32 v144, v0
	v_mov_b32_e32 v145, v0
	v_mov_b32_e32 v146, v0
	v_mov_b32_e32 v147, v0
	.p2align 6

; __device__ __forceinline__ unsigned cvt_pk_bf16(float lo, float hi) { unsigned r; asm volatile("v_cvt_pk_bf16_f32 %0, %1, %2" : "=v"(r) : "v"(lo), "v"(hi)); return r; }
; __device__ __forceinline__ float bflo(unsigned w) { return __uint_as_float(w << 16); }
; __device__ __forceinline__ float bfhi(unsigned w) { return __uint_as_float(w & 0xffff0000u); }
; __device__ __forceinline__ float silu_f(float z) { return z / (1.0f + __expf(-z)); }
; __device__ __forceinline__ float sigmoid_f(float z) { return 1.0f / (1.0f + __expf(-z)); }
;     __device__ __forceinline__ void operator()(const AccT& acc, const Unit& u, int wr, int wc, int fr, int fq) const {
;     ...
;                 const int row = u.pm * 256 + ai * 128 + wr * 64 + m * 16 + fr;
;                 const u32x4 z = *(const u32x4*)(PROJ + (size_t)row * PP + C_ZS + lc);
;                 const f32x4 l0 = acc[ai][0][m][0] + bl0, l1 = acc[ai][0][m][1] + bl1, g0 = acc[ai][1][m][0] + bg0, g1 = acc[ai][1][m][1] + bg1;
;                 float o[8];
;                 o[0] = l0[0] * sigmoid_f(g0[0]) * silu_f(bflo(z.x)); o[1] = l0[1] * sigmoid_f(g0[1]) * silu_f(bfhi(z.x));
;                 o[2] = l0[2] * sigmoid_f(g0[2]) * silu_f(bflo(z.y)); o[3] = l0[3] * sigmoid_f(g0[3]) * silu_f(bfhi(z.y));
;                 o[4] = l1[0] * sigmoid_f(g1[0]) * silu_f(bflo(z.z)); o[5] = l1[1] * sigmoid_f(g1[1]) * silu_f(bfhi(z.z));
;                 o[6] = l1[2] * sigmoid_f(g1[2]) * silu_f(bflo(z.w)); o[7] = l1[3] * sigmoid_f(g1[3]) * silu_f(bfhi(z.w));
;                 u32x4 w; w.x = cvt_pk_bf16(o[0], o[1]); w.y = cvt_pk_bf16(o[2], o[3]); w.z = cvt_pk_bf16(o[4], o[5]); w.w = cvt_pk_bf16(o[6], o[7]);
;                 *(u32x4*)(OCAT + (size_t)row * 2048 + 1024 + lc) = w;
.LBB0_609:
	v_lshl_or_b32 v128, s38, 7, v166
	v_ashrrev_i32_e32 v129, 31, v128
	v_lshl_add_u32 v168, s37, 8, v164
	v_mov_b64_e32 v[160:161], s[6:7]
	v_lshlrev_b64 v[16:17], 2, v[128:129]
	v_mad_i64_i32 v[162:163], s[30:31], v168, s52, v[160:161]
	v_lshlrev_b64 v[158:159], 1, v[128:129]
	v_lshl_add_u64 v[18:19], s[16:17], 0, v[16:17]
	v_lshl_add_u64 v[20:21], s[18:19], 0, v[16:17]
	v_lshl_add_u64 v[128:129], v[162:163], 0, v[158:159]
	global_load_dwordx4 v[24:27], v[18:19], off offset:16
	global_load_dwordx4 v[28:31], v[18:19], off
	s_nop 0
	global_load_dwordx4 v[16:19], v[20:21], off offset:16
	s_nop 0
	global_load_dwordx4 v[20:23], v[20:21], off
	v_add_co_u32_e32 v128, vcc, s63, v128
	s_nop 1
	v_addc_co_u32_e32 v129, vcc, 0, v129, vcc
	s_mov_b32 s82, 0x1b8000
	s_mov_b32 s83, 0
	v_lshl_add_u64 v[204:205], v[128:129], 0, s[82:83]
	global_load_dwordx4 v[204:207], v[204:205], off
	v_mov_b32_e32 v176, 0xbfb8aa3b
	v_mov_b32_e32 v177, 0xbfb8aa3b
	s_waitcnt vmcnt(1)
	v_pk_add_f32 v[144:145], v[144:145], v[28:29]
	v_pk_add_f32 v[146:147], v[146:147], v[30:31]
	v_pk_add_f32 v[140:141], v[140:141], v[24:25]
	v_pk_add_f32 v[142:143], v[142:143], v[26:27]
	v_pk_add_f32 v[136:137], v[136:137], v[20:21]
	v_pk_add_f32 v[138:139], v[138:139], v[22:23]
	v_pk_add_f32 v[132:133], v[132:133], v[16:17]
	v_pk_add_f32 v[134:135], v[134:135], v[18:19]
	v_pk_mul_f32 v[136:137], v[136:137], v[176:177]
	v_pk_mul_f32 v[138:139], v[138:139], v[176:177]
	v_pk_mul_f32 v[132:133], v[132:133], v[176:177]
	v_pk_mul_f32 v[134:135], v[134:135], v[176:177]
	v_lshlrev_b32_e32 v178, 16, v216
	v_and_b32_e32 v179, 0xffff0000, v216
	v_lshlrev_b32_e32 v180, 16, v217
	v_and_b32_e32 v181, 0xffff0000, v217
	v_lshlrev_b32_e32 v182, 16, v218
	v_and_b32_e32 v183, 0xffff0000, v218
	v_lshlrev_b32_e32 v184, 16, v219
	v_and_b32_e32 v185, 0xffff0000, v219
	v_pk_mul_f32 v[186:187], v[178:179], v[176:177]
	v_pk_mul_f32 v[188:189], v[180:181], v[176:177]
	v_pk_mul_f32 v[190:191], v[182:183], v[176:177]
	v_pk_mul_f32 v[192:193], v[184:185], v[176:177]
	v_exp_f32_e32 v136, v136
	v_exp_f32_e32 v137, v137
	v_exp_f32_e32 v138, v138
	v_exp_f32_e32 v139, v139
	v_exp_f32_e32 v132, v132
	v_exp_f32_e32 v133, v133
	v_exp_f32_e32 v134, v134
	v_exp_f32_e32 v135, v135
	v_exp_f32_e32 v186, v186
	v_exp_f32_e32 v187, v187
	v_exp_f32_e32 v188, v188
	v_exp_f32_e32 v189, v189
	v_exp_f32_e32 v190, v190
	v_exp_f32_e32 v191, v191
	v_exp_f32_e32 v192, v192
	v_exp_f32_e32 v193, v193
	v_mad_i64_i32 v[174:175], s[30:31], v168, s66, v[162:163]
	v_lshl_add_u64 v[174:175], v[174:175], 0, v[158:159]
	v_add_co_u32_e32 v174, vcc, s67, v174
	s_nop 1
	v_addc_co_u32_e32 v175, vcc, 0, v175, vcc
	v_pk_add_f32 v[136:137], v[136:137], 1.0 op_sel_hi:[1,0]
	v_pk_add_f32 v[138:139], v[138:139], 1.0 op_sel_hi:[1,0]
	v_pk_add_f32 v[132:133], v[132:133], 1.0 op_sel_hi:[1,0]
	v_pk_add_f32 v[134:135], v[134:135], 1.0 op_sel_hi:[1,0]
	v_pk_add_f32 v[186:187], v[186:187], 1.0 op_sel_hi:[1,0]
	v_pk_add_f32 v[188:189], v[188:189], 1.0 op_sel_hi:[1,0]
	v_pk_add_f32 v[190:191], v[190:191], 1.0 op_sel_hi:[1,0]
	v_pk_add_f32 v[192:193], v[192:193], 1.0 op_sel_hi:[1,0]
	v_pk_mul_f32 v[186:187], v[186:187], v[136:137]
	v_pk_mul_f32 v[188:189], v[188:189], v[138:139]
	v_pk_mul_f32 v[190:191], v[190:191], v[132:133]
	v_pk_mul_f32 v[192:193], v[192:193], v[134:135]
	v_rcp_f32_e32 v186, v186
	v_rcp_f32_e32 v187, v187
	v_rcp_f32_e32 v188, v188
	v_rcp_f32_e32 v189, v189
	v_rcp_f32_e32 v190, v190
	v_rcp_f32_e32 v191, v191
	v_rcp_f32_e32 v192, v192
	v_rcp_f32_e32 v193, v193
	v_pk_mul_f32 v[144:145], v[144:145], v[178:179]
	v_pk_mul_f32 v[146:147], v[146:147], v[180:181]
	v_pk_mul_f32 v[140:141], v[140:141], v[182:183]
	v_pk_mul_f32 v[142:143], v[142:143], v[184:185]
	v_pk_mul_f32 v[144:145], v[144:145], v[186:187]
	v_pk_mul_f32 v[146:147], v[146:147], v[188:189]
	v_pk_mul_f32 v[140:141], v[140:141], v[190:191]
	v_pk_mul_f32 v[142:143], v[142:143], v[192:193]
	v_cvt_pk_bf16_f32 v132, v144, v145
	v_cvt_pk_bf16_f32 v133, v146, v147
	v_cvt_pk_bf16_f32 v134, v140, v141
	v_cvt_pk_bf16_f32 v135, v142, v143
	global_store_dwordx4 v[174:175], v[132:135], off offset:2048
	v_pk_add_f32 v[124:125], v[124:125], v[28:29]
	v_pk_add_f32 v[126:127], v[126:127], v[30:31]
	v_pk_add_f32 v[120:121], v[120:121], v[24:25]
	v_pk_add_f32 v[122:123], v[122:123], v[26:27]
	v_pk_add_f32 v[116:117], v[116:117], v[20:21]
	v_pk_add_f32 v[118:119], v[118:119], v[22:23]
	v_pk_add_f32 v[112:113], v[112:113], v[16:17]
	v_pk_add_f32 v[114:115], v[114:115], v[18:19]
	v_pk_mul_f32 v[116:117], v[116:117], v[176:177]
	v_pk_mul_f32 v[118:119], v[118:119], v[176:177]
	v_pk_mul_f32 v[112:113], v[112:113], v[176:177]
	v_pk_mul_f32 v[114:115], v[114:115], v[176:177]
	v_lshlrev_b32_e32 v178, 16, v220
	v_and_b32_e32 v179, 0xffff0000, v220
	v_lshlrev_b32_e32 v180, 16, v221
	v_and_b32_e32 v181, 0xffff0000, v221
	v_lshlrev_b32_e32 v182, 16, v222
	v_and_b32_e32 v183, 0xffff0000, v222
	v_lshlrev_b32_e32 v184, 16, v223
	v_and_b32_e32 v185, 0xffff0000, v223
	v_pk_mul_f32 v[186:187], v[178:179], v[176:177]
	v_pk_mul_f32 v[188:189], v[180:181], v[176:177]
	v_pk_mul_f32 v[190:191], v[182:183], v[176:177]
	v_pk_mul_f32 v[192:193], v[184:185], v[176:177]
	v_exp_f32_e32 v116, v116
	v_exp_f32_e32 v117, v117
	v_exp_f32_e32 v118, v118
	v_exp_f32_e32 v119, v119
	v_exp_f32_e32 v112, v112
	v_exp_f32_e32 v113, v113
	v_exp_f32_e32 v114, v114
	v_exp_f32_e32 v115, v115
	v_exp_f32_e32 v186, v186
	v_exp_f32_e32 v187, v187
	v_exp_f32_e32 v188, v188
	v_exp_f32_e32 v189, v189
	v_exp_f32_e32 v190, v190
	v_exp_f32_e32 v191, v191
	v_exp_f32_e32 v192, v192
	v_exp_f32_e32 v193, v193
	v_or_b32_e32 v170, 16, v168
; __device__ __forceinline__ unsigned cvt_pk_bf16(float lo, float hi) { unsigned r; asm volatile("v_cvt_pk_bf16_f32 %0, %1, %2" : "=v"(r) : "v"(lo), "v"(hi)); return r; }
; __device__ __forceinline__ float bflo(unsigned w) { return __uint_as_float(w << 16); }
; __device__ __forceinline__ float bfhi(unsigned w) { return __uint_as_float(w & 0xffff0000u); }
; __device__ __forceinline__ float silu_f(float z) { return z / (1.0f + __expf(-z)); }
; __device__ __forceinline__ float sigmoid_f(float z) { return 1.0f / (1.0f + __expf(-z)); }
;     __device__ __forceinline__ void operator()(const AccT& acc, const Unit& u, int wr, int wc, int fr, int fq) const {
;     ...
;                 const int row = u.pm * 256 + ai * 128 + wr * 64 + m * 16 + fr;
;                 const u32x4 z = *(const u32x4*)(PROJ + (size_t)row * PP + C_ZS + lc);
;                 const f32x4 l0 = acc[ai][0][m][0] + bl0, l1 = acc[ai][0][m][1] + bl1, g0 = acc[ai][1][m][0] + bg0, g1 = acc[ai][1][m][1] + bg1;
;                 float o[8];
;                 o[0] = l0[0] * sigmoid_f(g0[0]) * silu_f(bflo(z.x)); o[1] = l0[1] * sigmoid_f(g0[1]) * silu_f(bfhi(z.x));
;                 o[2] = l0[2] * sigmoid_f(g0[2]) * silu_f(bflo(z.y)); o[3] = l0[3] * sigmoid_f(g0[3]) * silu_f(bfhi(z.y));
;                 o[4] = l1[0] * sigmoid_f(g1[0]) * silu_f(bflo(z.z)); o[5] = l1[1] * sigmoid_f(g1[1]) * silu_f(bfhi(z.z));
;                 o[6] = l1[2] * sigmoid_f(g1[2]) * silu_f(bflo(z.w)); o[7] = l1[3] * sigmoid_f(g1[3]) * silu_f(bfhi(z.w));
;                 u32x4 w; w.x = cvt_pk_bf16(o[0], o[1]); w.y = cvt_pk_bf16(o[2], o[3]); w.z = cvt_pk_bf16(o[4], o[5]); w.w = cvt_pk_bf16(o[6], o[7]);
;                 *(u32x4*)(OCAT + (size_t)row * 2048 + 1024 + lc) = w;
	v_mad_i64_i32 v[172:173], s[30:31], v170, s52, v[160:161]
	v_mad_i64_i32 v[174:175], s[30:31], v170, s66, v[172:173]
	v_lshl_add_u64 v[174:175], v[174:175], 0, v[158:159]
	v_add_co_u32_e32 v174, vcc, s67, v174
	s_nop 1
	v_addc_co_u32_e32 v175, vcc, 0, v175, vcc
	v_pk_add_f32 v[116:117], v[116:117], 1.0 op_sel_hi:[1,0]
	v_pk_add_f32 v[118:119], v[118:119], 1.0 op_sel_hi:[1,0]
	v_pk_add_f32 v[112:113], v[112:113], 1.0 op_sel_hi:[1,0]
	v_pk_add_f32 v[114:115], v[114:115], 1.0 op_sel_hi:[1,0]
	v_pk_add_f32 v[186:187], v[186:187], 1.0 op_sel_hi:[1,0]
	v_pk_add_f32 v[188:189], v[188:189], 1.0 op_sel_hi:[1,0]
	v_pk_add_f32 v[190:191], v[190:191], 1.0 op_sel_hi:[1,0]
	v_pk_add_f32 v[192:193], v[192:193], 1.0 op_sel_hi:[1,0]
	v_pk_mul_f32 v[186:187], v[186:187], v[116:117]
	v_pk_mul_f32 v[188:189], v[188:189], v[118:119]
	v_pk_mul_f32 v[190:191], v[190:191], v[112:113]
	v_pk_mul_f32 v[192:193], v[192:193], v[114:115]
	v_rcp_f32_e32 v186, v186
	v_rcp_f32_e32 v187, v187
	v_rcp_f32_e32 v188, v188
	v_rcp_f32_e32 v189, v189
	v_rcp_f32_e32 v190, v190
	v_rcp_f32_e32 v191, v191
	v_rcp_f32_e32 v192, v192
	v_rcp_f32_e32 v193, v193
	v_pk_mul_f32 v[124:125], v[124:125], v[178:179]
	v_pk_mul_f32 v[126:127], v[126:127], v[180:181]
	v_pk_mul_f32 v[120:121], v[120:121], v[182:183]
	v_pk_mul_f32 v[122:123], v[122:123], v[184:185]
	v_pk_mul_f32 v[124:125], v[124:125], v[186:187]
	v_pk_mul_f32 v[126:127], v[126:127], v[188:189]
	v_pk_mul_f32 v[120:121], v[120:121], v[190:191]
	v_pk_mul_f32 v[122:123], v[122:123], v[192:193]
	v_cvt_pk_bf16_f32 v112, v124, v125
	v_cvt_pk_bf16_f32 v113, v126, v127
	v_cvt_pk_bf16_f32 v114, v120, v121
	v_cvt_pk_bf16_f32 v115, v122, v123
	global_store_dwordx4 v[174:175], v[112:115], off offset:2048
	v_pk_add_f32 v[108:109], v[108:109], v[28:29]
	v_pk_add_f32 v[110:111], v[110:111], v[30:31]
	v_pk_add_f32 v[104:105], v[104:105], v[24:25]
	v_pk_add_f32 v[106:107], v[106:107], v[26:27]
	v_pk_add_f32 v[100:101], v[100:101], v[20:21]
	v_pk_add_f32 v[102:103], v[102:103], v[22:23]
	v_pk_add_f32 v[96:97], v[96:97], v[16:17]
	v_pk_add_f32 v[98:99], v[98:99], v[18:19]
	v_pk_mul_f32 v[100:101], v[100:101], v[176:177]
	v_pk_mul_f32 v[102:103], v[102:103], v[176:177]
	v_pk_mul_f32 v[96:97], v[96:97], v[176:177]
	v_pk_mul_f32 v[98:99], v[98:99], v[176:177]
	v_lshlrev_b32_e32 v178, 16, v226
	v_and_b32_e32 v179, 0xffff0000, v226
	v_lshlrev_b32_e32 v180, 16, v227
	v_and_b32_e32 v181, 0xffff0000, v227
	v_lshlrev_b32_e32 v182, 16, v228
	v_and_b32_e32 v183, 0xffff0000, v228
	v_lshlrev_b32_e32 v184, 16, v229
	v_and_b32_e32 v185, 0xffff0000, v229
	v_pk_mul_f32 v[186:187], v[178:179], v[176:177]
	v_pk_mul_f32 v[188:189], v[180:181], v[176:177]
	v_pk_mul_f32 v[190:191], v[182:183], v[176:177]
	v_pk_mul_f32 v[192:193], v[184:185], v[176:177]
	v_exp_f32_e32 v100, v100
	v_exp_f32_e32 v101, v101
	v_exp_f32_e32 v102, v102
	v_exp_f32_e32 v103, v103
	v_exp_f32_e32 v96, v96
	v_exp_f32_e32 v97, v97
	v_exp_f32_e32 v98, v98
	v_exp_f32_e32 v99, v99
	v_exp_f32_e32 v186, v186
	v_exp_f32_e32 v187, v187
	v_exp_f32_e32 v188, v188
	v_exp_f32_e32 v189, v189
	v_exp_f32_e32 v190, v190
	v_exp_f32_e32 v191, v191
	v_exp_f32_e32 v192, v192
	v_exp_f32_e32 v193, v193
	v_or_b32_e32 v170, 32, v168
	v_mad_i64_i32 v[172:173], s[30:31], v170, s52, v[160:161]
	v_mad_i64_i32 v[174:175], s[30:31], v170, s66, v[172:173]
	v_lshl_add_u64 v[174:175], v[174:175], 0, v[158:159]
	v_add_co_u32_e32 v174, vcc, s67, v174
	s_nop 1
	v_addc_co_u32_e32 v175, vcc, 0, v175, vcc
	v_pk_add_f32 v[100:101], v[100:101], 1.0 op_sel_hi:[1,0]
	v_pk_add_f32 v[102:103], v[102:103], 1.0 op_sel_hi:[1,0]
	v_pk_add_f32 v[96:97], v[96:97], 1.0 op_sel_hi:[1,0]
	v_pk_add_f32 v[98:99], v[98:99], 1.0 op_sel_hi:[1,0]
	v_pk_add_f32 v[186:187], v[186:187], 1.0 op_sel_hi:[1,0]
	v_pk_add_f32 v[188:189], v[188:189], 1.0 op_sel_hi:[1,0]
	v_pk_add_f32 v[190:191], v[190:191], 1.0 op_sel_hi:[1,0]
	v_pk_add_f32 v[192:193], v[192:193], 1.0 op_sel_hi:[1,0]
	v_pk_mul_f32 v[186:187], v[186:187], v[100:101]
	v_pk_mul_f32 v[188:189], v[188:189], v[102:103]
	v_pk_mul_f32 v[190:191], v[190:191], v[96:97]
	v_pk_mul_f32 v[192:193], v[192:193], v[98:99]
	v_rcp_f32_e32 v186, v186
	v_rcp_f32_e32 v187, v187
	v_rcp_f32_e32 v188, v188
	v_rcp_f32_e32 v189, v189
	v_rcp_f32_e32 v190, v190
	v_rcp_f32_e32 v191, v191
	v_rcp_f32_e32 v192, v192
	v_rcp_f32_e32 v193, v193
	v_pk_mul_f32 v[108:109], v[108:109], v[178:179]
	v_pk_mul_f32 v[110:111], v[110:111], v[180:181]
	v_pk_mul_f32 v[104:105], v[104:105], v[182:183]
	v_pk_mul_f32 v[106:107], v[106:107], v[184:185]
	v_pk_mul_f32 v[108:109], v[108:109], v[186:187]
	v_pk_mul_f32 v[110:111], v[110:111], v[188:189]
	v_pk_mul_f32 v[104:105], v[104:105], v[190:191]
	v_pk_mul_f32 v[106:107], v[106:107], v[192:193]
	v_cvt_pk_bf16_f32 v96, v108, v109
	v_cvt_pk_bf16_f32 v97, v110, v111
	v_cvt_pk_bf16_f32 v98, v104, v105
	v_cvt_pk_bf16_f32 v99, v106, v107
	global_store_dwordx4 v[174:175], v[96:99], off offset:2048
	v_pk_add_f32 v[92:93], v[92:93], v[28:29]
	v_pk_add_f32 v[94:95], v[94:95], v[30:31]
	v_pk_add_f32 v[88:89], v[88:89], v[24:25]
	v_pk_add_f32 v[90:91], v[90:91], v[26:27]
	v_pk_add_f32 v[84:85], v[84:85], v[20:21]
	v_pk_add_f32 v[86:87], v[86:87], v[22:23]
	v_pk_add_f32 v[80:81], v[80:81], v[16:17]
	v_pk_add_f32 v[82:83], v[82:83], v[18:19]
	v_pk_mul_f32 v[84:85], v[84:85], v[176:177]
	v_pk_mul_f32 v[86:87], v[86:87], v[176:177]
	v_pk_mul_f32 v[80:81], v[80:81], v[176:177]
	v_pk_mul_f32 v[82:83], v[82:83], v[176:177]
	v_lshlrev_b32_e32 v178, 16, v236
	v_and_b32_e32 v179, 0xffff0000, v236
	v_lshlrev_b32_e32 v180, 16, v237
	v_and_b32_e32 v181, 0xffff0000, v237
	v_lshlrev_b32_e32 v182, 16, v238
	v_and_b32_e32 v183, 0xffff0000, v238
; __device__ __forceinline__ unsigned cvt_pk_bf16(float lo, float hi) { unsigned r; asm volatile("v_cvt_pk_bf16_f32 %0, %1, %2" : "=v"(r) : "v"(lo), "v"(hi)); return r; }
; __device__ __forceinline__ float bflo(unsigned w) { return __uint_as_float(w << 16); }
; __device__ __forceinline__ float bfhi(unsigned w) { return __uint_as_float(w & 0xffff0000u); }
; __device__ __forceinline__ float silu_f(float z) { return z / (1.0f + __expf(-z)); }
; __device__ __forceinline__ float sigmoid_f(float z) { return 1.0f / (1.0f + __expf(-z)); }
;     __device__ __forceinline__ void operator()(const AccT& acc, const Unit& u, int wr, int wc, int fr, int fq) const {
;     ...
;                 const int row = u.pm * 256 + ai * 128 + wr * 64 + m * 16 + fr;
;                 const u32x4 z = *(const u32x4*)(PROJ + (size_t)row * PP + C_ZS + lc);
;                 const f32x4 l0 = acc[ai][0][m][0] + bl0, l1 = acc[ai][0][m][1] + bl1, g0 = acc[ai][1][m][0] + bg0, g1 = acc[ai][1][m][1] + bg1;
;                 float o[8];
;                 o[0] = l0[0] * sigmoid_f(g0[0]) * silu_f(bflo(z.x)); o[1] = l0[1] * sigmoid_f(g0[1]) * silu_f(bfhi(z.x));
;                 o[2] = l0[2] * sigmoid_f(g0[2]) * silu_f(bflo(z.y)); o[3] = l0[3] * sigmoid_f(g0[3]) * silu_f(bfhi(z.y));
;                 o[4] = l1[0] * sigmoid_f(g1[0]) * silu_f(bflo(z.z)); o[5] = l1[1] * sigmoid_f(g1[1]) * silu_f(bfhi(z.z));
;                 o[6] = l1[2] * sigmoid_f(g1[2]) * silu_f(bflo(z.w)); o[7] = l1[3] * sigmoid_f(g1[3]) * silu_f(bfhi(z.w));
;                 u32x4 w; w.x = cvt_pk_bf16(o[0], o[1]); w.y = cvt_pk_bf16(o[2], o[3]); w.z = cvt_pk_bf16(o[4], o[5]); w.w = cvt_pk_bf16(o[6], o[7]);
;                 *(u32x4*)(OCAT + (size_t)row * 2048 + 1024 + lc) = w;
	v_lshlrev_b32_e32 v184, 16, v239
	v_and_b32_e32 v185, 0xffff0000, v239
	v_pk_mul_f32 v[186:187], v[178:179], v[176:177]
	v_pk_mul_f32 v[188:189], v[180:181], v[176:177]
	v_pk_mul_f32 v[190:191], v[182:183], v[176:177]
	v_pk_mul_f32 v[192:193], v[184:185], v[176:177]
	v_exp_f32_e32 v84, v84
	v_exp_f32_e32 v85, v85
	v_exp_f32_e32 v86, v86
	v_exp_f32_e32 v87, v87
	v_exp_f32_e32 v80, v80
	v_exp_f32_e32 v81, v81
	v_exp_f32_e32 v82, v82
	v_exp_f32_e32 v83, v83
	v_exp_f32_e32 v186, v186
	v_exp_f32_e32 v187, v187
	v_exp_f32_e32 v188, v188
	v_exp_f32_e32 v189, v189
	v_exp_f32_e32 v190, v190
	v_exp_f32_e32 v191, v191
	v_exp_f32_e32 v192, v192
	v_exp_f32_e32 v193, v193
	v_or_b32_e32 v170, 48, v168
	v_mad_i64_i32 v[172:173], s[30:31], v170, s52, v[160:161]
	v_mad_i64_i32 v[174:175], s[30:31], v170, s66, v[172:173]
	v_lshl_add_u64 v[174:175], v[174:175], 0, v[158:159]
	v_add_co_u32_e32 v174, vcc, s67, v174
	s_nop 1
	v_addc_co_u32_e32 v175, vcc, 0, v175, vcc
	v_pk_add_f32 v[84:85], v[84:85], 1.0 op_sel_hi:[1,0]
	v_pk_add_f32 v[86:87], v[86:87], 1.0 op_sel_hi:[1,0]
	v_pk_add_f32 v[80:81], v[80:81], 1.0 op_sel_hi:[1,0]
	v_pk_add_f32 v[82:83], v[82:83], 1.0 op_sel_hi:[1,0]
	v_pk_add_f32 v[186:187], v[186:187], 1.0 op_sel_hi:[1,0]
	v_pk_add_f32 v[188:189], v[188:189], 1.0 op_sel_hi:[1,0]
	v_pk_add_f32 v[190:191], v[190:191], 1.0 op_sel_hi:[1,0]
	v_pk_add_f32 v[192:193], v[192:193], 1.0 op_sel_hi:[1,0]
	v_pk_mul_f32 v[186:187], v[186:187], v[84:85]
	v_pk_mul_f32 v[188:189], v[188:189], v[86:87]
	v_pk_mul_f32 v[190:191], v[190:191], v[80:81]
	v_pk_mul_f32 v[192:193], v[192:193], v[82:83]
	v_rcp_f32_e32 v186, v186
	v_rcp_f32_e32 v187, v187
	v_rcp_f32_e32 v188, v188
	v_rcp_f32_e32 v189, v189
	v_rcp_f32_e32 v190, v190
	v_rcp_f32_e32 v191, v191
	v_rcp_f32_e32 v192, v192
	v_rcp_f32_e32 v193, v193
	v_pk_mul_f32 v[92:93], v[92:93], v[178:179]
	v_pk_mul_f32 v[94:95], v[94:95], v[180:181]
	v_pk_mul_f32 v[88:89], v[88:89], v[182:183]
	v_pk_mul_f32 v[90:91], v[90:91], v[184:185]
	v_pk_mul_f32 v[92:93], v[92:93], v[186:187]
	v_pk_mul_f32 v[94:95], v[94:95], v[188:189]
	v_pk_mul_f32 v[88:89], v[88:89], v[190:191]
	v_pk_mul_f32 v[90:91], v[90:91], v[192:193]
	v_cvt_pk_bf16_f32 v80, v92, v93
	v_cvt_pk_bf16_f32 v81, v94, v95
	v_cvt_pk_bf16_f32 v82, v88, v89
	v_cvt_pk_bf16_f32 v83, v90, v91
	global_store_dwordx4 v[174:175], v[80:83], off offset:2048
	v_pk_add_f32 v[76:77], v[76:77], v[28:29]
	v_pk_add_f32 v[78:79], v[78:79], v[30:31]
	v_pk_add_f32 v[72:73], v[72:73], v[24:25]
	v_pk_add_f32 v[74:75], v[74:75], v[26:27]
	v_pk_add_f32 v[68:69], v[68:69], v[20:21]
	v_pk_add_f32 v[70:71], v[70:71], v[22:23]
	v_pk_add_f32 v[64:65], v[64:65], v[16:17]
	v_pk_add_f32 v[66:67], v[66:67], v[18:19]
	v_pk_mul_f32 v[68:69], v[68:69], v[176:177]
	v_pk_mul_f32 v[70:71], v[70:71], v[176:177]
	v_pk_mul_f32 v[64:65], v[64:65], v[176:177]
	v_pk_mul_f32 v[66:67], v[66:67], v[176:177]
	v_lshlrev_b32_e32 v178, 16, v240
	v_and_b32_e32 v179, 0xffff0000, v240
	v_lshlrev_b32_e32 v180, 16, v241
	v_and_b32_e32 v181, 0xffff0000, v241
	v_lshlrev_b32_e32 v182, 16, v242
	v_and_b32_e32 v183, 0xffff0000, v242
	v_lshlrev_b32_e32 v184, 16, v243
	v_and_b32_e32 v185, 0xffff0000, v243
	v_pk_mul_f32 v[186:187], v[178:179], v[176:177]
	v_pk_mul_f32 v[188:189], v[180:181], v[176:177]
	v_pk_mul_f32 v[190:191], v[182:183], v[176:177]
	v_pk_mul_f32 v[192:193], v[184:185], v[176:177]
	v_exp_f32_e32 v68, v68
	v_exp_f32_e32 v69, v69
	v_exp_f32_e32 v70, v70
	v_exp_f32_e32 v71, v71
	v_exp_f32_e32 v64, v64
	v_exp_f32_e32 v65, v65
	v_exp_f32_e32 v66, v66
	v_exp_f32_e32 v67, v67
	v_exp_f32_e32 v186, v186
	v_exp_f32_e32 v187, v187
	v_exp_f32_e32 v188, v188
	v_exp_f32_e32 v189, v189
	v_exp_f32_e32 v190, v190
	v_exp_f32_e32 v191, v191
	v_exp_f32_e32 v192, v192
	v_exp_f32_e32 v193, v193
	v_add_u32_e32 v170, 0x80, v168
	v_mad_i64_i32 v[172:173], s[30:31], v170, s52, v[160:161]
	v_mad_i64_i32 v[174:175], s[30:31], v170, s66, v[172:173]
	v_lshl_add_u64 v[174:175], v[174:175], 0, v[158:159]
	v_add_co_u32_e32 v174, vcc, s67, v174
	s_nop 1
	v_addc_co_u32_e32 v175, vcc, 0, v175, vcc
	v_pk_add_f32 v[68:69], v[68:69], 1.0 op_sel_hi:[1,0]
	v_pk_add_f32 v[70:71], v[70:71], 1.0 op_sel_hi:[1,0]
	v_pk_add_f32 v[64:65], v[64:65], 1.0 op_sel_hi:[1,0]
	v_pk_add_f32 v[66:67], v[66:67], 1.0 op_sel_hi:[1,0]
	v_pk_add_f32 v[186:187], v[186:187], 1.0 op_sel_hi:[1,0]
	v_pk_add_f32 v[188:189], v[188:189], 1.0 op_sel_hi:[1,0]
	v_pk_add_f32 v[190:191], v[190:191], 1.0 op_sel_hi:[1,0]
	v_pk_add_f32 v[192:193], v[192:193], 1.0 op_sel_hi:[1,0]
	v_pk_mul_f32 v[186:187], v[186:187], v[68:69]
	v_pk_mul_f32 v[188:189], v[188:189], v[70:71]
	v_pk_mul_f32 v[190:191], v[190:191], v[64:65]
	v_pk_mul_f32 v[192:193], v[192:193], v[66:67]
	v_rcp_f32_e32 v186, v186
	v_rcp_f32_e32 v187, v187
	v_rcp_f32_e32 v188, v188
	v_rcp_f32_e32 v189, v189
	v_rcp_f32_e32 v190, v190
	v_rcp_f32_e32 v191, v191
	v_rcp_f32_e32 v192, v192
	v_rcp_f32_e32 v193, v193
	v_pk_mul_f32 v[76:77], v[76:77], v[178:179]
	v_pk_mul_f32 v[78:79], v[78:79], v[180:181]
	v_pk_mul_f32 v[72:73], v[72:73], v[182:183]
	v_pk_mul_f32 v[74:75], v[74:75], v[184:185]
	v_pk_mul_f32 v[76:77], v[76:77], v[186:187]
	v_pk_mul_f32 v[78:79], v[78:79], v[188:189]
	v_pk_mul_f32 v[72:73], v[72:73], v[190:191]
	v_pk_mul_f32 v[74:75], v[74:75], v[192:193]
	v_cvt_pk_bf16_f32 v64, v76, v77
	v_cvt_pk_bf16_f32 v65, v78, v79
	v_cvt_pk_bf16_f32 v66, v72, v73
	v_cvt_pk_bf16_f32 v67, v74, v75
	global_store_dwordx4 v[174:175], v[64:67], off offset:2048
	v_pk_add_f32 v[60:61], v[60:61], v[28:29]
	v_pk_add_f32 v[62:63], v[62:63], v[30:31]
	v_pk_add_f32 v[56:57], v[56:57], v[24:25]
	v_pk_add_f32 v[58:59], v[58:59], v[26:27]
; __device__ __forceinline__ unsigned cvt_pk_bf16(float lo, float hi) { unsigned r; asm volatile("v_cvt_pk_bf16_f32 %0, %1, %2" : "=v"(r) : "v"(lo), "v"(hi)); return r; }
; __device__ __forceinline__ float bflo(unsigned w) { return __uint_as_float(w << 16); }
; __device__ __forceinline__ float bfhi(unsigned w) { return __uint_as_float(w & 0xffff0000u); }
; __device__ __forceinline__ float silu_f(float z) { return z / (1.0f + __expf(-z)); }
; __device__ __forceinline__ float sigmoid_f(float z) { return 1.0f / (1.0f + __expf(-z)); }
;     __device__ __forceinline__ void operator()(const AccT& acc, const Unit& u, int wr, int wc, int fr, int fq) const {
;     ...
;                 const int row = u.pm * 256 + ai * 128 + wr * 64 + m * 16 + fr;
;                 const u32x4 z = *(const u32x4*)(PROJ + (size_t)row * PP + C_ZS + lc);
;                 const f32x4 l0 = acc[ai][0][m][0] + bl0, l1 = acc[ai][0][m][1] + bl1, g0 = acc[ai][1][m][0] + bg0, g1 = acc[ai][1][m][1] + bg1;
;                 float o[8];
;                 o[0] = l0[0] * sigmoid_f(g0[0]) * silu_f(bflo(z.x)); o[1] = l0[1] * sigmoid_f(g0[1]) * silu_f(bfhi(z.x));
;                 o[2] = l0[2] * sigmoid_f(g0[2]) * silu_f(bflo(z.y)); o[3] = l0[3] * sigmoid_f(g0[3]) * silu_f(bfhi(z.y));
;                 o[4] = l1[0] * sigmoid_f(g1[0]) * silu_f(bflo(z.z)); o[5] = l1[1] * sigmoid_f(g1[1]) * silu_f(bfhi(z.z));
;                 o[6] = l1[2] * sigmoid_f(g1[2]) * silu_f(bflo(z.w)); o[7] = l1[3] * sigmoid_f(g1[3]) * silu_f(bfhi(z.w));
;                 u32x4 w; w.x = cvt_pk_bf16(o[0], o[1]); w.y = cvt_pk_bf16(o[2], o[3]); w.z = cvt_pk_bf16(o[4], o[5]); w.w = cvt_pk_bf16(o[6], o[7]);
;                 *(u32x4*)(OCAT + (size_t)row * 2048 + 1024 + lc) = w;
	v_pk_add_f32 v[52:53], v[52:53], v[20:21]
	v_pk_add_f32 v[54:55], v[54:55], v[22:23]
	v_pk_add_f32 v[48:49], v[48:49], v[16:17]
	v_pk_add_f32 v[50:51], v[50:51], v[18:19]
	v_pk_mul_f32 v[52:53], v[52:53], v[176:177]
	v_pk_mul_f32 v[54:55], v[54:55], v[176:177]
	v_pk_mul_f32 v[48:49], v[48:49], v[176:177]
	v_pk_mul_f32 v[50:51], v[50:51], v[176:177]
	v_lshlrev_b32_e32 v178, 16, v244
	v_and_b32_e32 v179, 0xffff0000, v244
	v_lshlrev_b32_e32 v180, 16, v245
	v_and_b32_e32 v181, 0xffff0000, v245
	v_lshlrev_b32_e32 v182, 16, v246
	v_and_b32_e32 v183, 0xffff0000, v246
	v_lshlrev_b32_e32 v184, 16, v247
	v_and_b32_e32 v185, 0xffff0000, v247
	v_pk_mul_f32 v[186:187], v[178:179], v[176:177]
	v_pk_mul_f32 v[188:189], v[180:181], v[176:177]
	v_pk_mul_f32 v[190:191], v[182:183], v[176:177]
	v_pk_mul_f32 v[192:193], v[184:185], v[176:177]
	v_exp_f32_e32 v52, v52
	v_exp_f32_e32 v53, v53
	v_exp_f32_e32 v54, v54
	v_exp_f32_e32 v55, v55
	v_exp_f32_e32 v48, v48
	v_exp_f32_e32 v49, v49
	v_exp_f32_e32 v50, v50
	v_exp_f32_e32 v51, v51
	v_exp_f32_e32 v186, v186
	v_exp_f32_e32 v187, v187
	v_exp_f32_e32 v188, v188
	v_exp_f32_e32 v189, v189
	v_exp_f32_e32 v190, v190
	v_exp_f32_e32 v191, v191
	v_exp_f32_e32 v192, v192
	v_exp_f32_e32 v193, v193
	v_add_u32_e32 v170, 0x90, v168
	v_mad_i64_i32 v[172:173], s[30:31], v170, s52, v[160:161]
	v_mad_i64_i32 v[174:175], s[30:31], v170, s66, v[172:173]
	v_lshl_add_u64 v[174:175], v[174:175], 0, v[158:159]
	v_add_co_u32_e32 v174, vcc, s67, v174
	s_nop 1
	v_addc_co_u32_e32 v175, vcc, 0, v175, vcc
	v_pk_add_f32 v[52:53], v[52:53], 1.0 op_sel_hi:[1,0]
	v_pk_add_f32 v[54:55], v[54:55], 1.0 op_sel_hi:[1,0]
	v_pk_add_f32 v[48:49], v[48:49], 1.0 op_sel_hi:[1,0]
	v_pk_add_f32 v[50:51], v[50:51], 1.0 op_sel_hi:[1,0]
	v_pk_add_f32 v[186:187], v[186:187], 1.0 op_sel_hi:[1,0]
	v_pk_add_f32 v[188:189], v[188:189], 1.0 op_sel_hi:[1,0]
	v_pk_add_f32 v[190:191], v[190:191], 1.0 op_sel_hi:[1,0]
	v_pk_add_f32 v[192:193], v[192:193], 1.0 op_sel_hi:[1,0]
	v_pk_mul_f32 v[186:187], v[186:187], v[52:53]
	v_pk_mul_f32 v[188:189], v[188:189], v[54:55]
	v_pk_mul_f32 v[190:191], v[190:191], v[48:49]
	v_pk_mul_f32 v[192:193], v[192:193], v[50:51]
	v_rcp_f32_e32 v186, v186
	v_rcp_f32_e32 v187, v187
	v_rcp_f32_e32 v188, v188
	v_rcp_f32_e32 v189, v189
	v_rcp_f32_e32 v190, v190
	v_rcp_f32_e32 v191, v191
	v_rcp_f32_e32 v192, v192
	v_rcp_f32_e32 v193, v193
	v_pk_mul_f32 v[60:61], v[60:61], v[178:179]
	v_pk_mul_f32 v[62:63], v[62:63], v[180:181]
	v_pk_mul_f32 v[56:57], v[56:57], v[182:183]
	v_pk_mul_f32 v[58:59], v[58:59], v[184:185]
	v_pk_mul_f32 v[60:61], v[60:61], v[186:187]
	v_pk_mul_f32 v[62:63], v[62:63], v[188:189]
	v_pk_mul_f32 v[56:57], v[56:57], v[190:191]
	v_pk_mul_f32 v[58:59], v[58:59], v[192:193]
	v_cvt_pk_bf16_f32 v48, v60, v61
	v_cvt_pk_bf16_f32 v49, v62, v63
	v_cvt_pk_bf16_f32 v50, v56, v57
	v_cvt_pk_bf16_f32 v51, v58, v59
	global_store_dwordx4 v[174:175], v[48:51], off offset:2048
	v_pk_add_f32 v[44:45], v[44:45], v[28:29]
	v_pk_add_f32 v[46:47], v[46:47], v[30:31]
	v_pk_add_f32 v[40:41], v[40:41], v[24:25]
	v_pk_add_f32 v[42:43], v[42:43], v[26:27]
	v_pk_add_f32 v[36:37], v[36:37], v[20:21]
	v_pk_add_f32 v[38:39], v[38:39], v[22:23]
	v_pk_add_f32 v[32:33], v[32:33], v[16:17]
	v_pk_add_f32 v[34:35], v[34:35], v[18:19]
	v_pk_mul_f32 v[36:37], v[36:37], v[176:177]
	v_pk_mul_f32 v[38:39], v[38:39], v[176:177]
	v_pk_mul_f32 v[32:33], v[32:33], v[176:177]
	v_pk_mul_f32 v[34:35], v[34:35], v[176:177]
	v_lshlrev_b32_e32 v178, 16, v248
	v_and_b32_e32 v179, 0xffff0000, v248
	v_lshlrev_b32_e32 v180, 16, v249
	v_and_b32_e32 v181, 0xffff0000, v249
	v_lshlrev_b32_e32 v182, 16, v250
	v_and_b32_e32 v183, 0xffff0000, v250
	v_lshlrev_b32_e32 v184, 16, v251
	v_and_b32_e32 v185, 0xffff0000, v251
	v_pk_mul_f32 v[186:187], v[178:179], v[176:177]
	v_pk_mul_f32 v[188:189], v[180:181], v[176:177]
	v_pk_mul_f32 v[190:191], v[182:183], v[176:177]
	v_pk_mul_f32 v[192:193], v[184:185], v[176:177]
	v_exp_f32_e32 v36, v36
	v_exp_f32_e32 v37, v37
	v_exp_f32_e32 v38, v38
	v_exp_f32_e32 v39, v39
	v_exp_f32_e32 v32, v32
	v_exp_f32_e32 v33, v33
	v_exp_f32_e32 v34, v34
	v_exp_f32_e32 v35, v35
	v_exp_f32_e32 v186, v186
	v_exp_f32_e32 v187, v187
	v_exp_f32_e32 v188, v188
	v_exp_f32_e32 v189, v189
	v_exp_f32_e32 v190, v190
	v_exp_f32_e32 v191, v191
	v_exp_f32_e32 v192, v192
	v_exp_f32_e32 v193, v193
	v_add_u32_e32 v170, 0xa0, v168
	v_mad_i64_i32 v[172:173], s[30:31], v170, s52, v[160:161]
	v_mad_i64_i32 v[174:175], s[30:31], v170, s66, v[172:173]
	v_lshl_add_u64 v[174:175], v[174:175], 0, v[158:159]
	v_add_co_u32_e32 v174, vcc, s67, v174
	s_nop 1
	v_addc_co_u32_e32 v175, vcc, 0, v175, vcc
	v_pk_add_f32 v[36:37], v[36:37], 1.0 op_sel_hi:[1,0]
	v_pk_add_f32 v[38:39], v[38:39], 1.0 op_sel_hi:[1,0]
	v_pk_add_f32 v[32:33], v[32:33], 1.0 op_sel_hi:[1,0]
	v_pk_add_f32 v[34:35], v[34:35], 1.0 op_sel_hi:[1,0]
	v_pk_add_f32 v[186:187], v[186:187], 1.0 op_sel_hi:[1,0]
	v_pk_add_f32 v[188:189], v[188:189], 1.0 op_sel_hi:[1,0]
	v_pk_add_f32 v[190:191], v[190:191], 1.0 op_sel_hi:[1,0]
	v_pk_add_f32 v[192:193], v[192:193], 1.0 op_sel_hi:[1,0]
	v_pk_mul_f32 v[186:187], v[186:187], v[36:37]
	v_pk_mul_f32 v[188:189], v[188:189], v[38:39]
	v_pk_mul_f32 v[190:191], v[190:191], v[32:33]
	v_pk_mul_f32 v[192:193], v[192:193], v[34:35]
	v_rcp_f32_e32 v186, v186
	v_rcp_f32_e32 v187, v187
	v_rcp_f32_e32 v188, v188
	v_rcp_f32_e32 v189, v189
	v_rcp_f32_e32 v190, v190
	v_rcp_f32_e32 v191, v191
	v_rcp_f32_e32 v192, v192
	v_rcp_f32_e32 v193, v193
	v_pk_mul_f32 v[44:45], v[44:45], v[178:179]
	v_pk_mul_f32 v[46:47], v[46:47], v[180:181]
	v_pk_mul_f32 v[40:41], v[40:41], v[182:183]
	v_pk_mul_f32 v[42:43], v[42:43], v[184:185]
	v_pk_mul_f32 v[44:45], v[44:45], v[186:187]
	v_pk_mul_f32 v[46:47], v[46:47], v[188:189]
	v_pk_mul_f32 v[40:41], v[40:41], v[190:191]
	v_pk_mul_f32 v[42:43], v[42:43], v[192:193]
	v_cvt_pk_bf16_f32 v32, v44, v45
	v_cvt_pk_bf16_f32 v33, v46, v47
	v_cvt_pk_bf16_f32 v34, v40, v41
	v_cvt_pk_bf16_f32 v35, v42, v43
	global_store_dwordx4 v[174:175], v[32:35], off offset:2048
	s_waitcnt vmcnt(7)
; __device__ __forceinline__ unsigned cvt_pk_bf16(float lo, float hi) { unsigned r; asm volatile("v_cvt_pk_bf16_f32 %0, %1, %2" : "=v"(r) : "v"(lo), "v"(hi)); return r; }
; __device__ __forceinline__ float bflo(unsigned w) { return __uint_as_float(w << 16); }
; __device__ __forceinline__ float bfhi(unsigned w) { return __uint_as_float(w & 0xffff0000u); }
; __device__ __forceinline__ float silu_f(float z) { return z / (1.0f + __expf(-z)); }
; __device__ __forceinline__ float sigmoid_f(float z) { return 1.0f / (1.0f + __expf(-z)); }
;     __device__ __forceinline__ void operator()(const AccT& acc, const Unit& u, int wr, int wc, int fr, int fq) const {
;     ...
;                 const f32x4 l0 = acc[ai][0][m][0] + bl0, l1 = acc[ai][0][m][1] + bl1, g0 = acc[ai][1][m][0] + bg0, g1 = acc[ai][1][m][1] + bg1;
;                 float o[8];
;                 o[0] = l0[0] * sigmoid_f(g0[0]) * silu_f(bflo(z.x)); o[1] = l0[1] * sigmoid_f(g0[1]) * silu_f(bfhi(z.x));
;                 o[2] = l0[2] * sigmoid_f(g0[2]) * silu_f(bflo(z.y)); o[3] = l0[3] * sigmoid_f(g0[3]) * silu_f(bfhi(z.y));
;                 o[4] = l1[0] * sigmoid_f(g1[0]) * silu_f(bflo(z.z)); o[5] = l1[1] * sigmoid_f(g1[1]) * silu_f(bfhi(z.z));
;                 o[6] = l1[2] * sigmoid_f(g1[2]) * silu_f(bflo(z.w)); o[7] = l1[3] * sigmoid_f(g1[3]) * silu_f(bfhi(z.w));
;                 u32x4 w; w.x = cvt_pk_bf16(o[0], o[1]); w.y = cvt_pk_bf16(o[2], o[3]); w.z = cvt_pk_bf16(o[4], o[5]); w.w = cvt_pk_bf16(o[6], o[7]);
;                 *(u32x4*)(OCAT + (size_t)row * 2048 + 1024 + lc) = w;
;                 if (m == 3) asm volatile("" ::: "memory");
	v_pk_add_f32 v[12:13], v[12:13], v[28:29]
	v_pk_add_f32 v[14:15], v[14:15], v[30:31]
	v_pk_add_f32 v[8:9], v[8:9], v[24:25]
	v_pk_add_f32 v[10:11], v[10:11], v[26:27]
	v_pk_add_f32 v[4:5], v[4:5], v[20:21]
	v_pk_add_f32 v[6:7], v[6:7], v[22:23]
	v_pk_add_f32 v[0:1], v[0:1], v[16:17]
	v_pk_add_f32 v[2:3], v[2:3], v[18:19]
	v_pk_mul_f32 v[4:5], v[4:5], v[176:177]
	v_pk_mul_f32 v[6:7], v[6:7], v[176:177]
	v_pk_mul_f32 v[0:1], v[0:1], v[176:177]
	v_pk_mul_f32 v[2:3], v[2:3], v[176:177]
	v_lshlrev_b32_e32 v178, 16, v204
	v_and_b32_e32 v179, 0xffff0000, v204
	v_lshlrev_b32_e32 v180, 16, v205
	v_and_b32_e32 v181, 0xffff0000, v205
	v_lshlrev_b32_e32 v182, 16, v206
	v_and_b32_e32 v183, 0xffff0000, v206
	v_lshlrev_b32_e32 v184, 16, v207
	v_and_b32_e32 v185, 0xffff0000, v207
	v_pk_mul_f32 v[186:187], v[178:179], v[176:177]
	v_pk_mul_f32 v[188:189], v[180:181], v[176:177]
	v_pk_mul_f32 v[190:191], v[182:183], v[176:177]
	v_pk_mul_f32 v[192:193], v[184:185], v[176:177]
	v_exp_f32_e32 v4, v4
	v_exp_f32_e32 v5, v5
	v_exp_f32_e32 v6, v6
	v_exp_f32_e32 v7, v7
	v_exp_f32_e32 v0, v0
	v_exp_f32_e32 v1, v1
	v_exp_f32_e32 v2, v2
	v_exp_f32_e32 v3, v3
	v_exp_f32_e32 v186, v186
	v_exp_f32_e32 v187, v187
	v_exp_f32_e32 v188, v188
	v_exp_f32_e32 v189, v189
	v_exp_f32_e32 v190, v190
	v_exp_f32_e32 v191, v191
	v_exp_f32_e32 v192, v192
	v_exp_f32_e32 v193, v193
	v_add_u32_e32 v170, 0xb0, v168
	v_mad_i64_i32 v[172:173], s[30:31], v170, s52, v[160:161]
	v_mad_i64_i32 v[174:175], s[30:31], v170, s66, v[172:173]
	v_lshl_add_u64 v[174:175], v[174:175], 0, v[158:159]
	v_add_co_u32_e32 v174, vcc, 0xca00000, v174
	s_nop 1
	v_addc_co_u32_e32 v175, vcc, 0, v175, vcc
	v_pk_add_f32 v[4:5], v[4:5], 1.0 op_sel_hi:[1,0]
	v_pk_add_f32 v[6:7], v[6:7], 1.0 op_sel_hi:[1,0]
	v_pk_add_f32 v[0:1], v[0:1], 1.0 op_sel_hi:[1,0]
	v_pk_add_f32 v[2:3], v[2:3], 1.0 op_sel_hi:[1,0]
	v_pk_add_f32 v[186:187], v[186:187], 1.0 op_sel_hi:[1,0]
	v_pk_add_f32 v[188:189], v[188:189], 1.0 op_sel_hi:[1,0]
	v_pk_add_f32 v[190:191], v[190:191], 1.0 op_sel_hi:[1,0]
	v_pk_add_f32 v[192:193], v[192:193], 1.0 op_sel_hi:[1,0]
	v_pk_mul_f32 v[186:187], v[186:187], v[4:5]
	v_pk_mul_f32 v[188:189], v[188:189], v[6:7]
	v_pk_mul_f32 v[190:191], v[190:191], v[0:1]
	v_pk_mul_f32 v[192:193], v[192:193], v[2:3]
	v_rcp_f32_e32 v186, v186
	v_rcp_f32_e32 v187, v187
	v_rcp_f32_e32 v188, v188
	v_rcp_f32_e32 v189, v189
	v_rcp_f32_e32 v190, v190
	v_rcp_f32_e32 v191, v191
	v_rcp_f32_e32 v192, v192
	v_rcp_f32_e32 v193, v193
	v_pk_mul_f32 v[12:13], v[12:13], v[178:179]
	v_pk_mul_f32 v[14:15], v[14:15], v[180:181]
	v_pk_mul_f32 v[8:9], v[8:9], v[182:183]
	v_pk_mul_f32 v[10:11], v[10:11], v[184:185]
	v_pk_mul_f32 v[12:13], v[12:13], v[186:187]
	v_pk_mul_f32 v[14:15], v[14:15], v[188:189]
	v_pk_mul_f32 v[8:9], v[8:9], v[190:191]
	v_pk_mul_f32 v[10:11], v[10:11], v[192:193]
	v_cvt_pk_bf16_f32 v0, v12, v13
	v_cvt_pk_bf16_f32 v1, v14, v15
	v_cvt_pk_bf16_f32 v2, v8, v9
	v_cvt_pk_bf16_f32 v3, v10, v11
	s_mov_b64 s[30:31], -1
	global_store_dwordx4 v[174:175], v[0:3], off offset:2048
	s_andn2_b64 vcc, exec, s[4:5]
	s_cbranch_vccnz .LBB0_598
	s_andn2_b64 vcc, exec, s[8:9]
	s_cbranch_vccnz .LBB0_597
	s_barrier
	s_branch .LBB0_597
